# attention epilogue: packed f32 multiplies replaced by scalar pairs (packed ops are slow next to MFMAs)
# speedup vs baseline: 1.0061x; 1.0016x over previous
.Lopt_done:
	s_mov_b32 s78, 0
	v_mov_b32_e32 v1, v244
	v_lshlrev_b32_e32 v98, 5, v206
	v_bfe_u32 v157, v1, 5, 1
	v_and_b32_e32 v156, 31, v1
	v_lshlrev_b32_e32 v66, 9, v157
	v_mov_b32_e32 v67, v0
	v_lshl_add_u64 v[66:67], s[38:39], 0, v[66:67]
	v_lshlrev_b32_e32 v68, 4, v156
	v_mov_b32_e32 v69, v0
	v_ashrrev_i32_e32 v99, 31, v98
	v_lshl_add_u64 v[100:101], v[66:67], 0, v[68:69]
	v_lshlrev_b64 v[66:67], 10, v[98:99]
	v_lshl_add_u64 v[74:75], v[100:101], 0, v[66:67]
	global_load_dwordx4 v[66:69], v[74:75], off
	v_or_b32_e32 v70, 8, v98
	v_ashrrev_i32_e32 v71, 31, v70
	v_lshlrev_b64 v[70:71], 10, v[70:71]
	v_lshl_add_u64 v[76:77], v[100:101], 0, v[70:71]
	global_load_dwordx4 v[70:73], v[76:77], off
	global_load_dwordx4 v[102:105], v[74:75], off offset:1024
	global_load_dwordx4 v[106:109], v[76:77], off offset:1024
	global_load_dwordx4 v[110:113], v[74:75], off offset:2048
	global_load_dwordx4 v[114:117], v[76:77], off offset:2048
	global_load_dwordx4 v[118:121], v[74:75], off offset:3072
	v_and_b32_e32 v79, 64, v191
	v_xor_b32_e32 v78, 32, v191
	v_add_u32_e32 v79, 64, v79
	v_cmp_lt_i32_e32 vcc, v78, v79
	global_load_dwordx4 v[122:125], v[76:77], off offset:3072
	v_ashrrev_i32_e32 v158, 6, v1
	v_cndmask_b32_e32 v78, v191, v78, vcc
	v_lshlrev_b32_e32 v78, 2, v78
	ds_bpermute_b32 v78, v78, v173
	v_add_co_u32_e32 v134, vcc, s37, v74
	v_bfe_u32 v160, v1, 4, 2
	s_nop 0
	v_addc_co_u32_e32 v135, vcc, 0, v75, vcc
	s_waitcnt lgkmcnt(0)
	v_add_f32_e32 v74, v173, v78
	v_div_scale_f32 v75, s[8:9], v74, v74, 1.0
	v_add_co_u32_e32 v136, vcc, s37, v76
	global_load_dwordx4 v[126:129], v[134:135], off
	v_rcp_f32_e32 v76, v75
	v_addc_co_u32_e32 v137, vcc, 0, v77, vcc
	v_div_scale_f32 v77, vcc, 1.0, v74, 1.0
	v_fma_f32 v78, -v75, v76, 1.0
	v_fmac_f32_e32 v76, v78, v76
	v_mul_f32_e32 v78, v77, v76
	v_fma_f32 v79, -v75, v78, v77
	v_fmac_f32_e32 v78, v79, v76
	v_fma_f32 v75, -v75, v78, v77
	v_div_fmas_f32 v75, v75, v76, v78
	v_div_fixup_f32 v138, v75, v74, 1.0
	v_mul_f32_e32 v50, v138, v50
	v_mul_f32_e32 v51, v138, v51
	v_mul_f32_e32 v52, v138, v52
	v_mul_f32_e32 v53, v138, v53
	v_mul_f32_e32 v54, v138, v54
	v_mul_f32_e32 v55, v138, v55
	v_mul_f32_e32 v56, v138, v56
	v_mul_f32_e32 v57, v138, v57
	v_cvt_pk_bf16_f32 v50, v50, v51
	v_cvt_pk_bf16_f32 v51, v52, v53
	v_cvt_pk_bf16_f32 v52, v54, v55
	v_cvt_pk_bf16_f32 v53, v56, v57
	global_load_dwordx4 v[54:57], v[136:137], off
	global_load_dwordx4 v[130:133], v[134:135], off offset:1024
	v_mul_f32_e32 v58, v138, v58
	v_mul_f32_e32 v59, v138, v59
	v_mul_f32_e32 v60, v138, v60
	v_mul_f32_e32 v61, v138, v61
	v_mul_f32_e32 v62, v138, v62
	v_mul_f32_e32 v63, v138, v63
	v_mul_f32_e32 v64, v138, v64
	v_mul_f32_e32 v65, v138, v65
	v_cvt_pk_bf16_f32 v58, v58, v59
	v_cvt_pk_bf16_f32 v59, v60, v61
	v_cvt_pk_bf16_f32 v60, v62, v63
	v_cvt_pk_bf16_f32 v61, v64, v65
	v_mul_f32_e32 v34, v138, v34
	v_mul_f32_e32 v35, v138, v35
	v_mul_f32_e32 v36, v138, v36
	v_mul_f32_e32 v37, v138, v37
	v_mul_f32_e32 v38, v138, v38
	v_mul_f32_e32 v39, v138, v39
	v_mul_f32_e32 v40, v138, v40
	v_mul_f32_e32 v41, v138, v41
	v_mul_f32_e32 v42, v138, v42
	v_mul_f32_e32 v43, v138, v43
	v_mul_f32_e32 v44, v138, v44
	v_mul_f32_e32 v45, v138, v45
	v_mul_f32_e32 v46, v138, v46
	v_mul_f32_e32 v47, v138, v47
	v_mul_f32_e32 v48, v138, v48
	v_mul_f32_e32 v49, v138, v49
	v_mul_f32_e32 v18, v138, v18
	v_mul_f32_e32 v19, v138, v19
	v_mul_f32_e32 v20, v138, v20
	v_mul_f32_e32 v21, v138, v21
	v_mul_f32_e32 v22, v138, v22
	v_mul_f32_e32 v23, v138, v23
	v_mul_f32_e32 v24, v138, v24
	v_mul_f32_e32 v25, v138, v25
	v_mul_f32_e32 v26, v138, v26
	v_mul_f32_e32 v27, v138, v27
	v_mul_f32_e32 v28, v138, v28
	v_mul_f32_e32 v29, v138, v29
	v_mul_f32_e32 v30, v138, v30
	v_mul_f32_e32 v31, v138, v31
	v_mul_f32_e32 v32, v138, v32
	v_mul_f32_e32 v33, v138, v33
	v_mul_f32_e32 v2, v138, v2
	v_mul_f32_e32 v3, v138, v3
	v_mul_f32_e32 v4, v138, v4
	v_mul_f32_e32 v5, v138, v5
	s_waitcnt vmcnt(10)
	v_mfma_f32_32x32x16_bf16 v[82:97], v[66:69], v[50:53], 0
	v_mul_f32_e64 v6, v6, v138
	v_mul_f32_e64 v7, v7, v138
	v_mul_f32_e64 v8, v8, v138
	v_mul_f32_e64 v9, v9, v138
	v_mul_f32_e64 v10, v10, v138
	v_mul_f32_e64 v11, v11, v138
	v_ashrrev_i32_e32 v173, 31, v172
	v_lshlrev_b32_e32 v1, 4, v1
	v_and_b32_e32 v154, 0xf0, v1
	v_mov_b32_e32 v155, v0
	s_waitcnt vmcnt(9)
	v_mfma_f32_32x32x16_bf16 v[66:81], v[70:73], v[50:53], 0
	v_mul_lo_u32 v1, v158, s45
	v_add_u32_e32 v1, 0, v1
	s_mov_b32 s14, 0
	s_waitcnt vmcnt(8)
	v_mfma_f32_32x32x16_bf16 v[82:97], v[102:105], v[58:61], v[82:97]
	global_load_dwordx4 v[62:65], v[134:135], off offset:2048
	global_load_dwordx4 v[102:105], v[134:135], off offset:3072
	s_waitcnt vmcnt(9)
	v_mfma_f32_32x32x16_bf16 v[66:81], v[106:109], v[58:61], v[66:81]
	v_cvt_pk_bf16_f32 v106, v34, v35
	v_cvt_pk_bf16_f32 v107, v36, v37
	v_cvt_pk_bf16_f32 v108, v38, v39
	v_cvt_pk_bf16_f32 v109, v40, v41
	global_load_dwordx4 v[34:37], v[136:137], off offset:1024
	global_load_dwordx4 v[38:41], v[136:137], off offset:2048
	s_waitcnt vmcnt(10)
	v_mfma_f32_32x32x16_bf16 v[82:97], v[110:113], v[106:109], v[82:97]
	v_cvt_pk_bf16_f32 v110, v42, v43
	v_cvt_pk_bf16_f32 v111, v44, v45
	global_load_dwordx4 v[42:45], v[136:137], off offset:3072
	v_cvt_pk_bf16_f32 v112, v46, v47
	v_or_b32_e32 v46, 16, v98
	v_ashrrev_i32_e32 v47, 31, v46
	v_lshlrev_b64 v[46:47], 10, v[46:47]
	v_lshl_add_u64 v[134:135], v[100:101], 0, v[46:47]
	s_waitcnt vmcnt(10)
	v_mfma_f32_32x32x16_bf16 v[66:81], v[114:117], v[106:109], v[66:81]
	v_cvt_pk_bf16_f32 v113, v48, v49
	v_cvt_pk_bf16_f32 v114, v18, v19
	v_cvt_pk_bf16_f32 v115, v20, v21
	v_cvt_pk_bf16_f32 v116, v22, v23
	v_cvt_pk_bf16_f32 v117, v24, v25
	global_load_dwordx4 v[18:21], v[134:135], off
	global_load_dwordx4 v[22:25], v[134:135], off offset:1024
	global_load_dwordx4 v[46:49], v[134:135], off offset:2048
	s_waitcnt vmcnt(12)
	v_mfma_f32_32x32x16_bf16 v[82:97], v[118:121], v[110:113], v[82:97]
	v_cvt_pk_bf16_f32 v118, v26, v27
	v_cvt_pk_bf16_f32 v119, v28, v29
	v_cvt_pk_bf16_f32 v120, v30, v31
	v_cvt_pk_bf16_f32 v121, v32, v33
	global_load_dwordx4 v[26:29], v[134:135], off offset:3072
	s_waitcnt vmcnt(12)
	v_mfma_f32_32x32x16_bf16 v[66:81], v[122:125], v[110:113], v[66:81]
	v_cvt_pk_bf16_f32 v122, v2, v3
	v_cvt_pk_bf16_f32 v123, v4, v5
	v_cvt_pk_bf16_f32 v124, v6, v7
	v_cvt_pk_bf16_f32 v125, v8, v9
	v_mul_f32_e64 v2, v12, v138
	v_mul_f32_e64 v3, v13, v138
	v_mul_f32_e32 v4, v138, v14
	v_mul_f32_e32 v5, v138, v15
	v_mul_f32_e32 v6, v138, v16
	v_mul_f32_e32 v7, v138, v17
	s_waitcnt vmcnt(11)
	v_mfma_f32_32x32x16_bf16 v[82:97], v[126:129], v[114:117], v[82:97]
	s_waitcnt vmcnt(10)
	v_mfma_f32_32x32x16_bf16 v[66:81], v[54:57], v[114:117], v[66:81]
	s_waitcnt vmcnt(9)
	v_mfma_f32_32x32x16_bf16 v[82:97], v[130:133], v[118:121], v[82:97]
	s_waitcnt vmcnt(6)
	v_mfma_f32_32x32x16_bf16 v[66:81], v[34:37], v[118:121], v[66:81]
	v_mfma_f32_32x32x16_bf16 v[82:97], v[62:65], v[122:125], v[82:97]
	v_cvt_pk_bf16_f32 v63, v2, v3
	v_add_co_u32_e32 v2, vcc, s37, v134
	v_cvt_pk_bf16_f32 v62, v10, v11
	s_nop 0
	v_addc_co_u32_e32 v3, vcc, 0, v135, vcc
	global_load_dwordx4 v[30:33], v[2:3], off
	global_load_dwordx4 v[34:37], v[2:3], off offset:1024
	s_waitcnt vmcnt(7)
	v_mfma_f32_32x32x16_bf16 v[66:81], v[38:41], v[122:125], v[66:81]
	v_cvt_pk_bf16_f32 v64, v4, v5
	v_cvt_pk_bf16_f32 v65, v6, v7
	s_waitcnt vmcnt(6)
	s_nop 0
	v_mfma_f32_32x32x16_bf16 v[66:81], v[42:45], v[62:65], v[66:81]
	global_load_dwordx4 v[38:41], v[2:3], off offset:2048
	global_load_dwordx4 v[42:45], v[2:3], off offset:3072
	s_waitcnt vmcnt(7)
	v_mfma_f32_32x32x16_bf16 v[2:17], v[18:21], v[50:53], 0
	v_or_b32_e32 v18, 24, v98
	v_ashrrev_i32_e32 v19, 31, v18
	v_lshlrev_b64 v[18:19], 10, v[18:19]
	v_lshl_add_u64 v[54:55], v[100:101], 0, v[18:19]
	global_load_dwordx4 v[18:21], v[54:55], off
	global_load_dwordx4 v[98:101], v[54:55], off offset:1024
	v_mfma_f32_32x32x16_bf16 v[82:97], v[102:105], v[62:65], v[82:97]
	global_load_dwordx4 v[102:105], v[54:55], off offset:2048
	global_load_dwordx4 v[126:129], v[54:55], off offset:3072
	s_waitcnt vmcnt(10)
	v_mfma_f32_32x32x16_bf16 v[2:17], v[22:25], v[58:61], v[2:17]
	v_add_co_u32_e32 v22, vcc, s37, v54
	v_mov_b32_e32 v24, s55
	s_nop 0
	v_addc_co_u32_e32 v23, vcc, 0, v55, vcc
	global_load_dwordx4 v[130:133], v[22:23], off
	global_load_dwordx4 v[134:137], v[22:23], off offset:1024
	global_load_dwordx4 v[138:141], v[22:23], off offset:2048
	global_load_dwordx4 v[142:145], v[22:23], off offset:3072
	s_waitcnt vmcnt(13)
	v_mfma_f32_32x32x16_bf16 v[2:17], v[46:49], v[106:109], v[2:17]
	v_lshlrev_b32_e32 v22, 5, v158
	v_and_b32_e32 v159, 0x60, v22
	v_lshlrev_b64 v[22:23], 12, v[172:173]
	v_bitop3_b32 v24, v159, s44, v24 bitop3:0xc8
	v_or3_b32 v22, v22, v24, v160
	v_lshlrev_b64 v[22:23], 8, v[22:23]
	s_waitcnt vmcnt(12)
	v_mfma_f32_32x32x16_bf16 v[2:17], v[26:29], v[110:113], v[2:17]
	s_waitcnt vmcnt(11)
	v_mfma_f32_32x32x16_bf16 v[2:17], v[30:33], v[114:117], v[2:17]
	s_waitcnt vmcnt(10)
	v_mfma_f32_32x32x16_bf16 v[2:17], v[34:37], v[118:121], v[2:17]
	v_lshl_add_u64 v[34:35], s[22:23], 0, v[22:23]
	v_lshl_add_u64 v[34:35], v[34:35], 0, v[154:155]
	s_waitcnt vmcnt(7)
	v_mfma_f32_32x32x16_bf16 v[18:33], v[18:21], v[50:53], 0
	global_load_dwordx4 v[146:149], v[34:35], off
	global_load_dwordx4 v[150:153], v[34:35], off offset:1024
	global_load_dwordx4 v[54:57], v[34:35], off offset:2048
	global_load_dwordx4 v[50:53], v[34:35], off offset:3072
	v_add_co_u32_e32 v34, vcc, s37, v34
	s_nop 1
	v_addc_co_u32_e32 v35, vcc, 0, v35, vcc
	s_waitcnt vmcnt(10)
	v_mfma_f32_32x32x16_bf16 v[18:33], v[98:101], v[58:61], v[18:33]
	v_mul_u32_u24_e32 v98, 0x110, v156
	v_lshlrev_b32_e32 v99, 5, v157
	v_cvt_pk_f16_f32 v58, v82, v83
	v_add3_u32 v82, v1, v98, v99
	v_cvt_pk_f16_f32 v59, v84, v85
	v_cvt_pk_f16_f32 v60, v86, v87
	v_cvt_pk_f16_f32 v61, v88, v89
	s_waitcnt vmcnt(9)
	v_mfma_f32_32x32x16_bf16 v[18:33], v[102:105], v[106:109], v[18:33]
	s_waitcnt vmcnt(8)
	v_mfma_f32_32x32x16_bf16 v[18:33], v[126:129], v[110:113], v[18:33]
	s_waitcnt vmcnt(7)
	v_mfma_f32_32x32x16_bf16 v[18:33], v[130:133], v[114:117], v[18:33]
	s_waitcnt vmcnt(6)
	v_mfma_f32_32x32x16_bf16 v[18:33], v[134:137], v[118:121], v[18:33]
	v_mfma_f32_32x32x16_bf16 v[2:17], v[38:41], v[122:125], v[2:17]
	s_waitcnt vmcnt(5)
	v_mfma_f32_32x32x16_bf16 v[18:33], v[138:141], v[122:125], v[18:33]
	v_mfma_f32_32x32x16_bf16 v[2:17], v[42:45], v[62:65], v[2:17]
	global_load_dwordx4 v[46:49], v[34:35], off
	global_load_dwordx4 v[42:45], v[34:35], off offset:1024
	global_load_dwordx4 v[38:41], v[34:35], off offset:2048
	s_nop 0
	global_load_dwordx4 v[34:37], v[34:35], off offset:3072
	ds_write_b128 v82, v[58:61] offset:49152
	v_cvt_pk_f16_f32 v58, v90, v91
	v_cvt_pk_f16_f32 v59, v92, v93
	v_cvt_pk_f16_f32 v60, v94, v95
	v_cvt_pk_f16_f32 v61, v96, v97
	ds_write_b128 v82, v[58:61] offset:49168
	s_waitcnt vmcnt(8)
	v_mfma_f32_32x32x16_bf16 v[18:33], v[142:145], v[62:65], v[18:33]
	v_cvt_pk_f16_f32 v2, v2, v3
	v_cvt_pk_f16_f32 v3, v4, v5
	v_cvt_pk_f16_f32 v4, v6, v7
	v_cvt_pk_f16_f32 v5, v8, v9
	ds_write_b128 v82, v[2:5] offset:49280
	v_cvt_pk_f16_f32 v2, v10, v11
	v_cvt_pk_f16_f32 v3, v12, v13
	v_cvt_pk_f16_f32 v4, v14, v15
	v_cvt_pk_f16_f32 v5, v16, v17
	ds_write_b128 v82, v[2:5] offset:49296
	s_nop 1
	v_cvt_pk_f16_f32 v2, v18, v19
	v_cvt_pk_f16_f32 v3, v20, v21
	v_cvt_pk_f16_f32 v4, v22, v23
	v_cvt_pk_f16_f32 v5, v24, v25
	v_cvt_pk_f16_f32 v58, v66, v67
	v_cvt_pk_f16_f32 v59, v68, v69
	v_cvt_pk_f16_f32 v60, v70, v71
	v_cvt_pk_f16_f32 v61, v72, v73
	ds_write_b128 v82, v[2:5] offset:49344
	v_cvt_pk_f16_f32 v2, v26, v27
	v_cvt_pk_f16_f32 v3, v28, v29
	v_cvt_pk_f16_f32 v4, v30, v31
	v_cvt_pk_f16_f32 v5, v32, v33
	ds_write_b128 v82, v[58:61] offset:49216
	v_cvt_pk_f16_f32 v58, v74, v75
	v_cvt_pk_f16_f32 v59, v76, v77
	v_cvt_pk_f16_f32 v60, v78, v79
	v_cvt_pk_f16_f32 v61, v80, v81
	ds_write_b128 v82, v[2:5] offset:49360
	v_mul_u32_u24_e32 v4, 0x110, v160
	ds_write_b128 v82, v[58:61] offset:49232
	v_add3_u32 v1, v1, v4, v154
	ds_read_b128 v[4:7], v1 offset:49152
	v_or3_b32 v2, v159, s55, v160
	v_mov_b32_e32 v3, v0
	v_lshlrev_b64 v[2:3], 12, v[2:3]
	v_lshlrev_b32_e32 v8, 7, v206
	v_lshl_add_u64 v[2:3], s[18:19], 0, v[2:3]
	v_ashrrev_i32_e32 v9, 31, v8
	v_lshl_add_u64 v[2:3], v[8:9], 1, v[2:3]
	ds_read_b128 v[8:11], v1 offset:50240
	s_waitcnt lgkmcnt(1)
	v_cvt_f32_f16_e32 v12, v4
	v_cvt_f32_f16_sdwa v13, v4 dst_sel:DWORD dst_unused:UNUSED_PAD src0_sel:WORD_1
	s_waitcnt vmcnt(7)
	v_lshlrev_b32_e32 v14, 16, v146
	v_and_b32_e32 v15, 0xffff0000, v146
	v_lshl_add_u64 v[2:3], v[2:3], 0, v[154:155]
	v_mul_f32_e32 v12, v14, v12
	v_mul_f32_e32 v13, v15, v13
	v_cvt_f32_f16_e32 v14, v5
	v_cvt_f32_f16_sdwa v15, v5 dst_sel:DWORD dst_unused:UNUSED_PAD src0_sel:WORD_1
	v_cvt_pk_bf16_f32 v4, v12, v13
	v_lshlrev_b32_e32 v12, 16, v147
	v_and_b32_e32 v13, 0xffff0000, v147
	v_mul_f32_e32 v12, v12, v14
	v_mul_f32_e32 v13, v13, v15
	v_cvt_f32_f16_e32 v14, v6
	v_cvt_f32_f16_sdwa v15, v6 dst_sel:DWORD dst_unused:UNUSED_PAD src0_sel:WORD_1
	v_cvt_pk_bf16_f32 v5, v12, v13
	v_lshlrev_b32_e32 v12, 16, v148
	v_and_b32_e32 v13, 0xffff0000, v148
	v_mul_f32_e32 v12, v12, v14
	v_mul_f32_e32 v13, v13, v15
	v_cvt_f32_f16_e32 v14, v7
	v_cvt_f32_f16_sdwa v15, v7 dst_sel:DWORD dst_unused:UNUSED_PAD src0_sel:WORD_1
	v_cvt_pk_bf16_f32 v6, v12, v13
	v_lshlrev_b32_e32 v12, 16, v149
	v_and_b32_e32 v13, 0xffff0000, v149
	v_mul_f32_e32 v12, v12, v14
	v_mul_f32_e32 v13, v13, v15
	v_add_co_u32_e32 v16, vcc, s16, v2
	v_cvt_pk_bf16_f32 v7, v12, v13
	global_store_dwordx4 v[2:3], v[4:7], off
	s_waitcnt lgkmcnt(0)
	v_cvt_f32_f16_e32 v12, v8
	v_cvt_f32_f16_sdwa v13, v8 dst_sel:DWORD dst_unused:UNUSED_PAD src0_sel:WORD_1
	v_cvt_f32_f16_e32 v6, v9
	v_cvt_f32_f16_sdwa v7, v9 dst_sel:DWORD dst_unused:UNUSED_PAD src0_sel:WORD_1
	s_waitcnt vmcnt(7)
	v_lshlrev_b32_e32 v8, 16, v151
	v_and_b32_e32 v9, 0xffff0000, v151
	v_lshlrev_b32_e32 v4, 16, v150
	v_mul_f32_e32 v6, v8, v6
	v_mul_f32_e32 v7, v9, v7
	v_cvt_f32_f16_e32 v8, v10
	v_cvt_f32_f16_sdwa v9, v10 dst_sel:DWORD dst_unused:UNUSED_PAD src0_sel:WORD_1
	v_and_b32_e32 v5, 0xffff0000, v150
	v_mul_f32_e32 v4, v4, v12
	v_mul_f32_e32 v5, v5, v13
	v_lshlrev_b32_e32 v10, 16, v153
	v_cvt_pk_bf16_f32 v4, v4, v5
	v_cvt_pk_bf16_f32 v5, v6, v7
	v_lshlrev_b32_e32 v6, 16, v152
	v_and_b32_e32 v7, 0xffff0000, v152
	v_mul_f32_e32 v6, v6, v8
	v_mul_f32_e32 v7, v7, v9
	v_cvt_f32_f16_e32 v8, v11
	v_cvt_f32_f16_sdwa v9, v11 dst_sel:DWORD dst_unused:UNUSED_PAD src0_sel:WORD_1
	v_and_b32_e32 v11, 0xffff0000, v153
	v_cvt_pk_bf16_f32 v6, v6, v7
	v_addc_co_u32_e32 v17, vcc, 0, v3, vcc
	v_mul_f32_e32 v8, v10, v8
	v_mul_f32_e32 v9, v11, v9
	ds_read_b128 v[12:15], v1 offset:52416
	v_cvt_pk_bf16_f32 v7, v8, v9
	ds_read_b128 v[8:11], v1 offset:51328
	global_store_dwordx4 v[16:17], v[4:7], off
	s_waitcnt lgkmcnt(0)
	v_cvt_f32_f16_e32 v18, v8
	v_cvt_f32_f16_e32 v6, v9
	v_cvt_f32_f16_sdwa v7, v9 dst_sel:DWORD dst_unused:UNUSED_PAD src0_sel:WORD_1
	v_cvt_f32_f16_sdwa v19, v8 dst_sel:DWORD dst_unused:UNUSED_PAD src0_sel:WORD_1
	s_waitcnt vmcnt(7)
	v_lshlrev_b32_e32 v8, 16, v55
	v_and_b32_e32 v9, 0xffff0000, v55
	v_mul_f32_e32 v6, v8, v6
	v_mul_f32_e32 v7, v9, v7
	v_cvt_f32_f16_e32 v8, v10
	v_cvt_f32_f16_sdwa v9, v10 dst_sel:DWORD dst_unused:UNUSED_PAD src0_sel:WORD_1
	v_lshlrev_b32_e32 v4, 16, v54
	v_and_b32_e32 v5, 0xffff0000, v54
	v_mul_f32_e32 v4, v4, v18
	v_mul_f32_e32 v5, v5, v19
	v_lshlrev_b32_e32 v10, 16, v57
	v_cvt_pk_bf16_f32 v4, v4, v5
	v_cvt_pk_bf16_f32 v5, v6, v7
	v_lshlrev_b32_e32 v6, 16, v56
	v_and_b32_e32 v7, 0xffff0000, v56
	v_mul_f32_e32 v6, v6, v8
	v_mul_f32_e32 v7, v7, v9
	v_cvt_f32_f16_e32 v8, v11
	v_cvt_f32_f16_sdwa v9, v11 dst_sel:DWORD dst_unused:UNUSED_PAD src0_sel:WORD_1
	v_and_b32_e32 v11, 0xffff0000, v57
	v_cvt_pk_bf16_f32 v6, v6, v7
	v_mul_f32_e32 v8, v10, v8
	v_mul_f32_e32 v9, v11, v9
	s_nop 0
	v_cvt_pk_bf16_f32 v7, v8, v9
	v_add_co_u32_e32 v8, vcc, s41, v2
	v_cvt_f32_f16_e32 v10, v12
	s_nop 0
	v_addc_co_u32_e32 v9, vcc, 0, v3, vcc
	global_store_dwordx4 v[8:9], v[4:7], off
	v_cvt_f32_f16_sdwa v11, v12 dst_sel:DWORD dst_unused:UNUSED_PAD src0_sel:WORD_1
	s_waitcnt vmcnt(7)
	v_lshlrev_b32_e32 v8, 16, v51
	v_cvt_f32_f16_e32 v6, v13
	v_cvt_f32_f16_sdwa v7, v13 dst_sel:DWORD dst_unused:UNUSED_PAD src0_sel:WORD_1
	v_and_b32_e32 v9, 0xffff0000, v51
	v_lshlrev_b32_e32 v4, 16, v50
	v_and_b32_e32 v5, 0xffff0000, v50
	v_mul_f32_e32 v6, v8, v6
	v_mul_f32_e32 v7, v9, v7
	v_cvt_f32_f16_e32 v8, v14
	v_cvt_f32_f16_sdwa v9, v14 dst_sel:DWORD dst_unused:UNUSED_PAD src0_sel:WORD_1
	v_mul_f32_e32 v4, v4, v10
	v_mul_f32_e32 v5, v5, v11
	v_lshlrev_b32_e32 v10, 16, v53
	v_cvt_pk_bf16_f32 v4, v4, v5
	v_cvt_pk_bf16_f32 v5, v6, v7
	v_lshlrev_b32_e32 v6, 16, v52
	v_and_b32_e32 v7, 0xffff0000, v52
	v_mul_f32_e32 v6, v6, v8
	v_mul_f32_e32 v7, v7, v9
	v_cvt_f32_f16_e32 v8, v15
	v_cvt_f32_f16_sdwa v9, v15 dst_sel:DWORD dst_unused:UNUSED_PAD src0_sel:WORD_1
	v_and_b32_e32 v11, 0xffff0000, v53
	v_cvt_pk_bf16_f32 v6, v6, v7
	v_add_co_u32_e32 v16, vcc, s50, v2
	v_mul_f32_e32 v8, v10, v8
	v_mul_f32_e32 v9, v11, v9
	s_nop 0
	v_addc_co_u32_e32 v17, vcc, 0, v3, vcc
	v_cvt_pk_bf16_f32 v7, v8, v9
	ds_read_b128 v[8:11], v1 offset:53504
	ds_read_b128 v[12:15], v1 offset:54592
	global_store_dwordx4 v[16:17], v[4:7], off
	s_waitcnt lgkmcnt(1)
	v_cvt_f32_f16_e32 v18, v8
	v_cvt_f32_f16_e32 v6, v9
	v_cvt_f32_f16_sdwa v7, v9 dst_sel:DWORD dst_unused:UNUSED_PAD src0_sel:WORD_1
	v_cvt_f32_f16_sdwa v19, v8 dst_sel:DWORD dst_unused:UNUSED_PAD src0_sel:WORD_1
	s_waitcnt vmcnt(7)
	v_lshlrev_b32_e32 v8, 16, v47
	v_and_b32_e32 v9, 0xffff0000, v47
	v_mul_f32_e32 v6, v8, v6
	v_mul_f32_e32 v7, v9, v7
	v_cvt_f32_f16_e32 v8, v10
	v_cvt_f32_f16_sdwa v9, v10 dst_sel:DWORD dst_unused:UNUSED_PAD src0_sel:WORD_1
	v_lshlrev_b32_e32 v4, 16, v46
	v_and_b32_e32 v5, 0xffff0000, v46
	v_mul_f32_e32 v4, v4, v18
	v_mul_f32_e32 v5, v5, v19
	v_lshlrev_b32_e32 v10, 16, v49
	v_cvt_pk_bf16_f32 v4, v4, v5
	v_cvt_pk_bf16_f32 v5, v6, v7
	v_lshlrev_b32_e32 v6, 16, v48
	v_and_b32_e32 v7, 0xffff0000, v48
	v_mul_f32_e32 v6, v6, v8
	v_mul_f32_e32 v7, v7, v9
	v_cvt_f32_f16_e32 v8, v11
	v_cvt_f32_f16_sdwa v9, v11 dst_sel:DWORD dst_unused:UNUSED_PAD src0_sel:WORD_1
	v_and_b32_e32 v11, 0xffff0000, v49
	v_cvt_pk_bf16_f32 v6, v6, v7
	v_mul_f32_e32 v8, v10, v8
	v_mul_f32_e32 v9, v11, v9
	s_nop 0
	v_cvt_pk_bf16_f32 v7, v8, v9
	v_add_co_u32_e32 v8, vcc, s51, v2
	s_waitcnt lgkmcnt(0)
	v_cvt_f32_f16_e32 v10, v12
	v_addc_co_u32_e32 v9, vcc, 0, v3, vcc
	global_store_dwordx4 v[8:9], v[4:7], off
	v_cvt_f32_f16_sdwa v11, v12 dst_sel:DWORD dst_unused:UNUSED_PAD src0_sel:WORD_1
	s_waitcnt vmcnt(7)
	v_lshlrev_b32_e32 v8, 16, v43
	v_cvt_f32_f16_e32 v6, v13
	v_cvt_f32_f16_sdwa v7, v13 dst_sel:DWORD dst_unused:UNUSED_PAD src0_sel:WORD_1
	v_and_b32_e32 v9, 0xffff0000, v43
	v_lshlrev_b32_e32 v4, 16, v42
	v_and_b32_e32 v5, 0xffff0000, v42
	v_mul_f32_e32 v6, v8, v6
	v_mul_f32_e32 v7, v9, v7
	v_cvt_f32_f16_e32 v8, v14
	v_cvt_f32_f16_sdwa v9, v14 dst_sel:DWORD dst_unused:UNUSED_PAD src0_sel:WORD_1
	v_mul_f32_e32 v4, v4, v10
	v_mul_f32_e32 v5, v5, v11
	v_lshlrev_b32_e32 v10, 16, v45
	v_cvt_pk_bf16_f32 v4, v4, v5
	v_cvt_pk_bf16_f32 v5, v6, v7
	v_lshlrev_b32_e32 v6, 16, v44
	v_and_b32_e32 v7, 0xffff0000, v44
	v_mul_f32_e32 v6, v6, v8
	v_mul_f32_e32 v7, v7, v9
	v_cvt_f32_f16_e32 v8, v15
	v_cvt_f32_f16_sdwa v9, v15 dst_sel:DWORD dst_unused:UNUSED_PAD src0_sel:WORD_1
	v_and_b32_e32 v11, 0xffff0000, v45
	v_cvt_pk_bf16_f32 v6, v6, v7
	v_add_co_u32_e32 v16, vcc, s52, v2
	v_mul_f32_e32 v8, v10, v8
	v_mul_f32_e32 v9, v11, v9
	s_nop 0
	v_addc_co_u32_e32 v17, vcc, 0, v3, vcc
	v_cvt_pk_bf16_f32 v7, v8, v9
	ds_read_b128 v[8:11], v1 offset:55680
	ds_read_b128 v[12:15], v1 offset:56768
	global_store_dwordx4 v[16:17], v[4:7], off
	s_waitcnt lgkmcnt(1)
	v_cvt_f32_f16_e32 v18, v8
	v_cvt_f32_f16_e32 v6, v9
	v_cvt_f32_f16_sdwa v7, v9 dst_sel:DWORD dst_unused:UNUSED_PAD src0_sel:WORD_1
	v_cvt_f32_f16_sdwa v19, v8 dst_sel:DWORD dst_unused:UNUSED_PAD src0_sel:WORD_1
	s_waitcnt vmcnt(7)
	v_lshlrev_b32_e32 v8, 16, v39
	v_and_b32_e32 v9, 0xffff0000, v39
	v_mul_f32_e32 v6, v8, v6
	v_mul_f32_e32 v7, v9, v7
	v_cvt_f32_f16_e32 v8, v10
	v_cvt_f32_f16_sdwa v9, v10 dst_sel:DWORD dst_unused:UNUSED_PAD src0_sel:WORD_1
	v_lshlrev_b32_e32 v4, 16, v38
	v_and_b32_e32 v5, 0xffff0000, v38
	v_mul_f32_e32 v4, v4, v18
	v_mul_f32_e32 v5, v5, v19
	v_lshlrev_b32_e32 v10, 16, v41
	v_cvt_pk_bf16_f32 v4, v4, v5
	v_cvt_pk_bf16_f32 v5, v6, v7
	v_lshlrev_b32_e32 v6, 16, v40
	v_and_b32_e32 v7, 0xffff0000, v40
	v_mul_f32_e32 v6, v6, v8
	v_mul_f32_e32 v7, v7, v9
	v_cvt_f32_f16_e32 v8, v11
	v_cvt_f32_f16_sdwa v9, v11 dst_sel:DWORD dst_unused:UNUSED_PAD src0_sel:WORD_1
	v_and_b32_e32 v11, 0xffff0000, v41
	v_cvt_pk_bf16_f32 v6, v6, v7
	v_mul_f32_e32 v8, v10, v8
	v_mul_f32_e32 v9, v11, v9
	s_nop 0
	v_cvt_pk_bf16_f32 v7, v8, v9
	v_add_co_u32_e32 v8, vcc, s53, v2
	s_waitcnt lgkmcnt(0)
	v_cvt_f32_f16_e32 v10, v12
	v_addc_co_u32_e32 v9, vcc, 0, v3, vcc
	global_store_dwordx4 v[8:9], v[4:7], off
	v_cvt_f32_f16_sdwa v11, v12 dst_sel:DWORD dst_unused:UNUSED_PAD src0_sel:WORD_1
	s_waitcnt vmcnt(7)
	v_lshlrev_b32_e32 v8, 16, v35
	v_cvt_f32_f16_e32 v6, v13
	v_cvt_f32_f16_sdwa v7, v13 dst_sel:DWORD dst_unused:UNUSED_PAD src0_sel:WORD_1
	v_and_b32_e32 v9, 0xffff0000, v35
	v_lshlrev_b32_e32 v4, 16, v34
	v_and_b32_e32 v5, 0xffff0000, v34
	v_mul_f32_e32 v6, v8, v6
	v_mul_f32_e32 v7, v9, v7
	v_cvt_f32_f16_e32 v8, v14
	v_cvt_f32_f16_sdwa v9, v14 dst_sel:DWORD dst_unused:UNUSED_PAD src0_sel:WORD_1
	v_mul_f32_e32 v4, v4, v10
	v_mul_f32_e32 v5, v5, v11
	v_lshlrev_b32_e32 v10, 16, v37
	v_cvt_pk_bf16_f32 v4, v4, v5
	v_cvt_pk_bf16_f32 v5, v6, v7
	v_lshlrev_b32_e32 v6, 16, v36
	v_and_b32_e32 v7, 0xffff0000, v36
	v_mul_f32_e32 v6, v6, v8
	v_mul_f32_e32 v7, v7, v9
	v_cvt_f32_f16_e32 v8, v15
	v_cvt_f32_f16_sdwa v9, v15 dst_sel:DWORD dst_unused:UNUSED_PAD src0_sel:WORD_1
	v_and_b32_e32 v11, 0xffff0000, v37
	v_add_co_u32_e32 v2, vcc, 0x1c000, v2
	v_mul_f32_e32 v8, v10, v8
	v_mul_f32_e32 v9, v11, v9
	v_cvt_pk_bf16_f32 v6, v6, v7
	v_cvt_pk_bf16_f32 v7, v8, v9
	v_addc_co_u32_e32 v3, vcc, 0, v3, vcc
	global_store_dwordx4 v[2:3], v[4:7], off
